# NSA selected+window loops: the 8 K-tile ds_reads issue right after the step barrier, before the DMA-issue/descriptor scalar blocks (LDS latency hidden under SALU work)
# baseline (speedup 1.0000x reference)
; #define LAS __attribute__((address_space(3)))
; #define MFMA32(a, b, c) __builtin_amdgcn_mfma_f32_32x32x16_bf16((a), (b), (c), 0, 0, 0)
; DI f32x16 co_qk1(LAS unsigned char* st, const bf16x8 (&qf)[8], int ka_in) {
;     const int ka = ka_in;
;     f32x16 S;
; #pragma unroll
;     for (int i = 0; i < 16; ++i) S[i] = 0.f;
;     __builtin_amdgcn_s_setprio(1);
; #pragma unroll
;     for (int ks = 0; ks < 8; ++ks) { const bf16x8 a = *(const LAS bf16x8*)(st + (ka ^ (32 * ks))); S = MFMA32(a, qf[ks], S); }
;     __builtin_amdgcn_s_setprio(0);
.LBB0_510:
	s_waitcnt lgkmcnt(0)
	s_barrier
	s_and_b32 s98, s76, 0xc000
	v_add_u32_e32 v252, s98, v162
	ds_read_b128 v[216:219], v252
	v_add_u32_e32 v252, s98, v164
	ds_read_b128 v[220:223], v252
	v_add_u32_e32 v252, s98, v165
	ds_read_b128 v[224:227], v252
	v_add_u32_e32 v252, s98, v166
	ds_read_b128 v[228:231], v252
	v_add_u32_e32 v252, s98, v167
	ds_read_b128 v[232:235], v252
	v_add_u32_e32 v252, s98, v168
	ds_read_b128 v[240:243], v252
	v_add_u32_e32 v252, s98, v169
	ds_read_b128 v[244:247], v252
	v_add_u32_e32 v252, s98, v170
	ds_read_b128 v[248:251], v252
	s_cmp_gt_i32 s77, s33
	s_cbranch_scc1 .LBB0_515
	v_cmp_gt_u32_e32 vcc, s46, v238
	v_readfirstlane_b32 s81, v238
	s_cbranch_vccnz .LBB0_513
	s_cmp_lt_u32 s81, 0x30000
	s_cselect_b32 s0, 0x4000, s51
	s_cselect_b32 s16, s50, 0x3c800000
	s_add_u32 s2, s73, s0
	s_addc_u32 s3, s74, 0
	s_movk_i32 s82, 0x7600
	s_movk_i32 s80, 0x1000
	s_mov_b64 s[8:9], s[16:17]
	s_mov_b64 s[40:41], s[20:21]
	s_branch .LBB0_514

; #define LAS __attribute__((address_space(3)))
; #define MFMA32(a, b, c) __builtin_amdgcn_mfma_f32_32x32x16_bf16((a), (b), (c), 0, 0, 0)
; DI f32x16 co_qk1(LAS unsigned char* st, const bf16x8 (&qf)[8], int ka_in) {
;     const int ka = ka_in;
;     f32x16 S;
; #pragma unroll
;     for (int i = 0; i < 16; ++i) S[i] = 0.f;
;     __builtin_amdgcn_s_setprio(1);
; #pragma unroll
;     for (int ks = 0; ks < 8; ++ks) { const bf16x8 a = *(const LAS bf16x8*)(st + (ka ^ (32 * ks))); S = MFMA32(a, qf[ks], S); }
;     __builtin_amdgcn_s_setprio(0);
;     return S;
.Lfast_win_orig:
	s_waitcnt lgkmcnt(0)
	v_add_u32_e32 v0, s16, v162
	ds_read_b128 v[2:5], v0
	v_add_u32_e32 v0, s16, v164
	ds_read_b128 v[6:9], v0
	v_add_u32_e32 v0, s16, v165
	s_waitcnt lgkmcnt(0)
	v_mfma_f32_32x32x16_bf16 v[96:111], v[2:5], v[112:115], 0
	ds_read_b128 v[2:5], v0
	v_add_u32_e32 v0, s16, v166
	v_mfma_f32_32x32x16_bf16 v[96:111], v[6:9], v[116:119], v[96:111]
	ds_read_b128 v[6:9], v0
	v_add_u32_e32 v0, s16, v167
	s_waitcnt lgkmcnt(0)
	v_mfma_f32_32x32x16_bf16 v[96:111], v[2:5], v[120:123], v[96:111]
	ds_read_b128 v[2:5], v0
	v_add_u32_e32 v0, s16, v168
	v_mfma_f32_32x32x16_bf16 v[96:111], v[6:9], v[124:127], v[96:111]
	ds_read_b128 v[6:9], v0
	v_add_u32_e32 v0, s16, v169
	s_waitcnt lgkmcnt(0)
	v_mfma_f32_32x32x16_bf16 v[96:111], v[2:5], v[128:131], v[96:111]
	ds_read_b128 v[2:5], v0
	v_add_u32_e32 v0, s16, v170
	v_mfma_f32_32x32x16_bf16 v[96:111], v[6:9], v[132:135], v[96:111]
	ds_read_b128 v[6:9], v0
	s_waitcnt lgkmcnt(0)
	v_mfma_f32_32x32x16_bf16 v[96:111], v[2:5], v[136:139], v[96:111]
	v_mfma_f32_32x32x16_bf16 v[96:111], v[6:9], v[140:143], v[96:111]
; #define LAS __attribute__((address_space(3)))
; DI float xh_max(float x) { const unsigned u = __float_as_uint(x); const auto r = __builtin_amdgcn_permlane32_swap(u, u, false, false); return fmaxf(__uint_as_float(r[0]), __uint_as_float(r[1])); }
; DI float xh_sum(float x) { const unsigned u = __float_as_uint(x); const auto r = __builtin_amdgcn_permlane32_swap(u, u, false, false); return __uint_as_float(r[0]) + __uint_as_float(r[1]); }
; template <int MODE>
; DI void co_finish(f32x16 S, LAS unsigned char* st, int key_base, AttnState& as, int tq, bool rowsel, int vb_in, int hh) {
;     const int vb = vb_in;
;     {
;         const int base = key_base + 4 * hh;
;         const int hi = (MODE == 0) ? (((tq - 31) >> 4) - base) : (tq - base);
;         const int lo = hi - 512;
; #pragma unroll
;         for (int i = 0; i < 16; ++i) { const int c = (i & 3) + 8 * (i >> 2); bool ok = (c <= hi); if (MODE == 2) ok = ok && (c > lo); if (MODE == 1) ok = ok && rowsel; S[i] = ok ? S[i] : -1e30f; }
;     }
;     float mx = S[0];
; #pragma unroll
;     for (int i = 1; i < 16; ++i) mx = fmaxf(mx, S[i]);
;     mx = xh_max(mx);
;     const float mxs = mx * SM_SCALE; const bool need = mxs > as.m + 8.f;
;     const float mnew = need ? mxs : as.m, muse = -fmaxf(mnew, -1e20f); float ps = 0.f;
; #pragma unroll
;     for (int i = 0; i < 16; ++i) { const float p = __builtin_amdgcn_exp2f(__builtin_fmaf(S[i], SM_SCALE, muse)); S[i] = p; ps += p; }
;     ps = xh_sum(ps);
;     if (__builtin_amdgcn_ballot_w64(need) != 0ull) {
;         const float alpha = __builtin_amdgcn_exp2f(as.m - mnew);
;         as.l *= alpha;
; #pragma unroll
;         for (int dt = 0; dt < 4; ++dt)
; #pragma unroll
;             for (int i = 0; i < 16; ++i) as.acc[dt][i] *= alpha;
;     }
;     as.l += ps; as.m = mnew;
.LBB0_517:
	s_waitcnt lgkmcnt(0)
	s_andn2_b64 vcc, exec, s[36:37]
	s_cbranch_vccnz .LBB0_521
	s_add_i32 s88, s72, s79
	s_sub_i32 s88, s88, 34
	s_cmp_lt_u32 s88, 0x1de
	s_cbranch_scc1 .Lfastf_win
	v_add_u32_e32 v0, s79, v145
	v_cmp_gt_u32_e32 vcc, s53, v0
	v_add_u32_e32 v3, -1, v0
	v_add_u32_e32 v4, -2, v0
	v_cndmask_b32_e32 v2, v153, v16, vcc
	v_cmp_gt_u32_e32 vcc, s53, v3
	v_add_u32_e32 v5, -3, v0
	v_add_u32_e32 v6, -8, v0
	v_cndmask_b32_e32 v3, v153, v17, vcc
	v_cmp_gt_u32_e32 vcc, s53, v4
	v_add_u32_e32 v7, -9, v0
	v_add_u32_e32 v8, -10, v0
	v_cndmask_b32_e32 v4, v153, v18, vcc
	v_cmp_gt_u32_e32 vcc, s53, v5
	v_add_u32_e32 v9, -11, v0
	v_add_u32_e32 v10, -16, v0
	v_cndmask_b32_e32 v5, v153, v19, vcc
	v_cmp_gt_u32_e32 vcc, s53, v6
	v_subrev_u32_e32 v11, 17, v0
	v_subrev_u32_e32 v12, 18, v0
	v_cndmask_b32_e32 v6, v153, v20, vcc
	v_cmp_gt_u32_e32 vcc, s53, v7
	v_subrev_u32_e32 v13, 19, v0
	v_subrev_u32_e32 v14, 24, v0
	v_cndmask_b32_e32 v7, v153, v21, vcc
	v_cmp_gt_u32_e32 vcc, s53, v8
	v_subrev_u32_e32 v15, 25, v0
	v_subrev_u32_e32 v176, 26, v0
	v_cndmask_b32_e32 v8, v153, v22, vcc
	v_cmp_gt_u32_e32 vcc, s53, v9
	v_subrev_u32_e32 v0, 27, v0
	s_nop 0
	v_cndmask_b32_e32 v9, v153, v23, vcc
	v_cmp_gt_u32_e32 vcc, s53, v10
	s_nop 1
	v_cndmask_b32_e32 v10, v153, v24, vcc
	v_cmp_gt_u32_e32 vcc, s53, v11
	s_nop 1
	v_cndmask_b32_e32 v11, v153, v25, vcc
	v_cmp_gt_u32_e32 vcc, s53, v12
	s_nop 1
	v_cndmask_b32_e32 v12, v153, v26, vcc
	v_cmp_gt_u32_e32 vcc, s53, v13
	s_nop 1
	v_cndmask_b32_e32 v13, v153, v27, vcc
	v_cmp_gt_u32_e32 vcc, s53, v14
	s_nop 1
	v_cndmask_b32_e32 v14, v153, v28, vcc
	v_cmp_gt_u32_e32 vcc, s53, v15
	s_nop 1
	v_cndmask_b32_e32 v15, v153, v29, vcc
	v_cmp_gt_u32_e32 vcc, s53, v176
	v_max_f32_e32 v176, v3, v3
	s_nop 0
	v_cndmask_b32_e32 v178, v153, v30, vcc
	v_cmp_gt_u32_e32 vcc, s53, v0
	v_max_f32_e32 v0, v2, v2
	v_max_f32_e32 v0, v0, v176
	v_max3_f32 v0, v0, v4, v5
	v_max3_f32 v0, v0, v6, v7
	v_max3_f32 v0, v0, v8, v9
	v_max3_f32 v0, v0, v10, v11
	v_max3_f32 v0, v0, v12, v13
	v_cndmask_b32_e32 v179, v153, v31, vcc
	v_max3_f32 v0, v0, v14, v15
	v_max3_f32 v0, v0, v178, v179
	v_mov_b32_e32 v176, v0
	s_nop 1
	v_permlane32_swap_b32_e32 v0, v176
	v_max_f32_e32 v176, v176, v176
	v_max_f32_e32 v0, v0, v0
	v_max_f32_e32 v0, v0, v176
	v_mul_f32_e32 v0, 0x3e0293ee, v0
	v_add_f32_e32 v176, 0x41000000, v177
	v_cmp_gt_f32_e32 vcc, v0, v176
	s_nop 1
	v_cndmask_b32_e32 v176, v177, v0, vcc
	v_max_f32_e32 v0, v176, v176
	v_max_f32_e32 v180, 0xe0ad78ec, v0
	v_fma_f32 v0, v2, s52, -v180
	v_exp_f32_e32 v0, v0
	v_fma_f32 v2, v3, s52, -v180
	v_exp_f32_e32 v2, v2
	v_fma_f32 v3, v4, s52, -v180
	v_exp_f32_e32 v3, v3
	v_fma_f32 v4, v5, s52, -v180
	v_exp_f32_e32 v4, v4
	v_add_f32_e32 v5, 0, v0
	v_add_f32_e32 v5, v2, v5
	v_add_f32_e32 v5, v3, v5
	v_add_f32_e32 v181, v4, v5
	v_fma_f32 v5, v6, s52, -v180
	v_exp_f32_e32 v5, v5
	v_fma_f32 v6, v7, s52, -v180
	v_exp_f32_e32 v6, v6
	v_fma_f32 v7, v8, s52, -v180
	v_exp_f32_e32 v7, v7
	v_fma_f32 v8, v9, s52, -v180
	v_exp_f32_e32 v8, v8
	v_add_f32_e32 v9, v5, v181
	v_add_f32_e32 v9, v6, v9
	v_add_f32_e32 v9, v7, v9
	v_add_f32_e32 v181, v8, v9
	v_fma_f32 v9, v10, s52, -v180
	v_exp_f32_e32 v9, v9
	v_fma_f32 v10, v11, s52, -v180
	v_exp_f32_e32 v10, v10
	v_fma_f32 v11, v12, s52, -v180
	v_exp_f32_e32 v11, v11
	v_fma_f32 v12, v13, s52, -v180
	v_exp_f32_e32 v12, v12
	v_add_f32_e32 v13, v9, v181
	v_add_f32_e32 v13, v10, v13
	v_add_f32_e32 v13, v11, v13
	v_add_f32_e32 v181, v12, v13
	v_fma_f32 v13, v14, s52, -v180
	v_exp_f32_e32 v13, v13
	v_fma_f32 v14, v15, s52, -v180
	v_exp_f32_e32 v14, v14
	v_fma_f32 v15, v178, s52, -v180
	v_exp_f32_e32 v15, v15
	v_fma_f32 v178, v179, s52, -v180
	v_exp_f32_e32 v178, v178
	v_add_f32_e32 v179, v13, v181
	v_add_f32_e32 v179, v14, v179
	v_add_f32_e32 v179, v15, v179
	v_add_f32_e32 v179, v178, v179
	v_mov_b32_e32 v180, v179
	s_nop 1
	v_permlane32_swap_b32_e32 v179, v180
	s_cbranch_vccz .LBB0_520
	v_sub_f32_e32 v177, v177, v176
	v_exp_f32_e32 v182, v177
	s_nop 0
	v_mul_f32_e32 v175, v175, v182
	v_pk_mul_f32 v[94:95], v[94:95], v[182:183] op_sel_hi:[1,0]
	v_pk_mul_f32 v[92:93], v[92:93], v[182:183] op_sel_hi:[1,0]
	v_pk_mul_f32 v[90:91], v[90:91], v[182:183] op_sel_hi:[1,0]
	v_pk_mul_f32 v[88:89], v[88:89], v[182:183] op_sel_hi:[1,0]
	v_pk_mul_f32 v[86:87], v[86:87], v[182:183] op_sel_hi:[1,0]
	v_pk_mul_f32 v[84:85], v[84:85], v[182:183] op_sel_hi:[1,0]
	v_pk_mul_f32 v[82:83], v[82:83], v[182:183] op_sel_hi:[1,0]
	v_pk_mul_f32 v[80:81], v[80:81], v[182:183] op_sel_hi:[1,0]
	v_pk_mul_f32 v[78:79], v[78:79], v[182:183] op_sel_hi:[1,0]
	v_pk_mul_f32 v[76:77], v[76:77], v[182:183] op_sel_hi:[1,0]
	v_pk_mul_f32 v[74:75], v[74:75], v[182:183] op_sel_hi:[1,0]
	v_pk_mul_f32 v[72:73], v[72:73], v[182:183] op_sel_hi:[1,0]
	v_pk_mul_f32 v[70:71], v[70:71], v[182:183] op_sel_hi:[1,0]
	v_pk_mul_f32 v[68:69], v[68:69], v[182:183] op_sel_hi:[1,0]
	v_pk_mul_f32 v[66:67], v[66:67], v[182:183] op_sel_hi:[1,0]
	v_pk_mul_f32 v[64:65], v[64:65], v[182:183] op_sel_hi:[1,0]
	v_pk_mul_f32 v[62:63], v[62:63], v[182:183] op_sel_hi:[1,0]
	v_pk_mul_f32 v[60:61], v[60:61], v[182:183] op_sel_hi:[1,0]
	v_pk_mul_f32 v[58:59], v[58:59], v[182:183] op_sel_hi:[1,0]
	v_pk_mul_f32 v[56:57], v[56:57], v[182:183] op_sel_hi:[1,0]
	v_pk_mul_f32 v[54:55], v[54:55], v[182:183] op_sel_hi:[1,0]
	v_pk_mul_f32 v[52:53], v[52:53], v[182:183] op_sel_hi:[1,0]
	v_pk_mul_f32 v[50:51], v[50:51], v[182:183] op_sel_hi:[1,0]
	v_pk_mul_f32 v[48:49], v[48:49], v[182:183] op_sel_hi:[1,0]
	v_pk_mul_f32 v[46:47], v[46:47], v[182:183] op_sel_hi:[1,0]
	v_pk_mul_f32 v[44:45], v[44:45], v[182:183] op_sel_hi:[1,0]
	v_pk_mul_f32 v[42:43], v[42:43], v[182:183] op_sel_hi:[1,0]
	v_pk_mul_f32 v[40:41], v[40:41], v[182:183] op_sel_hi:[1,0]
	v_pk_mul_f32 v[38:39], v[38:39], v[182:183] op_sel_hi:[1,0]
	v_pk_mul_f32 v[36:37], v[36:37], v[182:183] op_sel_hi:[1,0]
	v_pk_mul_f32 v[34:35], v[34:35], v[182:183] op_sel_hi:[1,0]
	v_pk_mul_f32 v[32:33], v[32:33], v[182:183] op_sel_hi:[1,0]

; #define LAS __attribute__((address_space(3)))
; #define MFMA32(a, b, c) __builtin_amdgcn_mfma_f32_32x32x16_bf16((a), (b), (c), 0, 0, 0)
; DI f32x16 co_qk1(LAS unsigned char* st, const bf16x8 (&qf)[8], int ka_in) {
;     const int ka = ka_in;
;     f32x16 S;
; #pragma unroll
;     for (int i = 0; i < 16; ++i) S[i] = 0.f;
;     __builtin_amdgcn_s_setprio(1);
; #pragma unroll
;     for (int ks = 0; ks < 8; ++ks) { const bf16x8 a = *(const LAS bf16x8*)(st + (ka ^ (32 * ks))); S = MFMA32(a, qf[ks], S); }
;     __builtin_amdgcn_s_setprio(0);
.Lsel_pf_ok:
	s_and_b32 s98, s72, 0xc000
	v_add_u32_e32 v252, s98, v162
	ds_read_b128 v[216:219], v252
	v_add_u32_e32 v252, s98, v164
	ds_read_b128 v[220:223], v252
	v_add_u32_e32 v252, s98, v165
	ds_read_b128 v[224:227], v252
	v_add_u32_e32 v252, s98, v166
	ds_read_b128 v[228:231], v252
	v_add_u32_e32 v252, s98, v167
	ds_read_b128 v[232:235], v252
	v_add_u32_e32 v252, s98, v168
	ds_read_b128 v[240:243], v252
	v_add_u32_e32 v252, s98, v169
	ds_read_b128 v[244:247], v252
	v_add_u32_e32 v252, s98, v170
	ds_read_b128 v[248:251], v252
	s_add_i32 s73, s41, 2
	s_cmp_ge_i32 s73, s33
	s_cbranch_scc1 .LBB0_546
	v_cmp_gt_u32_e32 vcc, s46, v238
	v_readfirstlane_b32 s76, v238
	s_cbranch_vccnz .LBB0_544
	s_cmp_lt_u32 s76, 0x30000
	s_cselect_b32 s16, s50, 0x3c800000
	s_cselect_b32 s3, s69, s66
	s_cselect_b32 s2, s68, s63
	s_movk_i32 s77, 0x7600
	s_movk_i32 s75, 0x1000
	s_mov_b64 s[8:9], s[16:17]
	s_mov_b64 s[40:41], s[20:21]
	s_branch .LBB0_545

; #define LAS __attribute__((address_space(3)))
; #define MFMA32(a, b, c) __builtin_amdgcn_mfma_f32_32x32x16_bf16((a), (b), (c), 0, 0, 0)
; DI f32x16 co_qk1(LAS unsigned char* st, const bf16x8 (&qf)[8], int ka_in) {
;     const int ka = ka_in;
;     f32x16 S;
; #pragma unroll
;     for (int i = 0; i < 16; ++i) S[i] = 0.f;
;     __builtin_amdgcn_s_setprio(1);
; #pragma unroll
;     for (int ks = 0; ks < 8; ++ks) { const bf16x8 a = *(const LAS bf16x8*)(st + (ka ^ (32 * ks))); S = MFMA32(a, qf[ks], S); }
;     __builtin_amdgcn_s_setprio(0);
;     return S;
.Lfast_sel_orig:
	s_waitcnt lgkmcnt(0)
	v_add_u32_e32 v0, s40, v162
	ds_read_b128 v[2:5], v0
	v_add_u32_e32 v0, s40, v164
	ds_read_b128 v[6:9], v0
	v_add_u32_e32 v0, s40, v165
	s_waitcnt lgkmcnt(0)
	v_mfma_f32_32x32x16_bf16 v[96:111], v[2:5], v[112:115], 0
	ds_read_b128 v[2:5], v0
	v_add_u32_e32 v0, s40, v166
	v_mfma_f32_32x32x16_bf16 v[96:111], v[6:9], v[116:119], v[96:111]
	ds_read_b128 v[6:9], v0
	v_add_u32_e32 v0, s40, v167
	s_waitcnt lgkmcnt(0)
	v_mfma_f32_32x32x16_bf16 v[96:111], v[2:5], v[120:123], v[96:111]
	ds_read_b128 v[2:5], v0
	v_add_u32_e32 v0, s40, v168
	v_mfma_f32_32x32x16_bf16 v[96:111], v[6:9], v[124:127], v[96:111]
	ds_read_b128 v[6:9], v0
	v_add_u32_e32 v0, s40, v169
	s_waitcnt lgkmcnt(0)
	v_mfma_f32_32x32x16_bf16 v[96:111], v[2:5], v[128:131], v[96:111]
	ds_read_b128 v[2:5], v0
	v_add_u32_e32 v0, s40, v170
	v_mfma_f32_32x32x16_bf16 v[96:111], v[6:9], v[132:135], v[96:111]
	ds_read_b128 v[6:9], v0
	s_waitcnt lgkmcnt(0)
	v_mfma_f32_32x32x16_bf16 v[96:111], v[2:5], v[136:139], v[96:111]
	v_mfma_f32_32x32x16_bf16 v[96:111], v[6:9], v[140:143], v[96:111]
; #define LAS __attribute__((address_space(3)))
; DI float xh_max(float x) { const unsigned u = __float_as_uint(x); const auto r = __builtin_amdgcn_permlane32_swap(u, u, false, false); return fmaxf(__uint_as_float(r[0]), __uint_as_float(r[1])); }
; DI float xh_sum(float x) { const unsigned u = __float_as_uint(x); const auto r = __builtin_amdgcn_permlane32_swap(u, u, false, false); return __uint_as_float(r[0]) + __uint_as_float(r[1]); }
; template <int MODE>
; DI void co_finish(f32x16 S, LAS unsigned char* st, int key_base, AttnState& as, int tq, bool rowsel, int vb_in, int hh) {
;     const int vb = vb_in;
;     {
;         const int base = key_base + 4 * hh;
;         const int hi = (MODE == 0) ? (((tq - 31) >> 4) - base) : (tq - base);
;         const int lo = hi - 512;
; #pragma unroll
;         for (int i = 0; i < 16; ++i) { const int c = (i & 3) + 8 * (i >> 2); bool ok = (c <= hi); if (MODE == 2) ok = ok && (c > lo); if (MODE == 1) ok = ok && rowsel; S[i] = ok ? S[i] : -1e30f; }
;     }
;     float mx = S[0];
; #pragma unroll
;     for (int i = 1; i < 16; ++i) mx = fmaxf(mx, S[i]);
;     mx = xh_max(mx);
;     const float mxs = mx * SM_SCALE; const bool need = mxs > as.m + 8.f;
;     const float mnew = need ? mxs : as.m, muse = -fmaxf(mnew, -1e20f); float ps = 0.f;
; #pragma unroll
;     for (int i = 0; i < 16; ++i) { const float p = __builtin_amdgcn_exp2f(__builtin_fmaf(S[i], SM_SCALE, muse)); S[i] = p; ps += p; }
;     ps = xh_sum(ps);
;     if (__builtin_amdgcn_ballot_w64(need) != 0ull) {
;         const float alpha = __builtin_amdgcn_exp2f(as.m - mnew);
;         as.l *= alpha;
; #pragma unroll
;         for (int dt = 0; dt < 4; ++dt)
; #pragma unroll
;             for (int i = 0; i < 16; ++i) as.acc[dt][i] *= alpha;
;     }
;     as.l += ps; as.m = mnew;
.LBB0_548:
	s_waitcnt lgkmcnt(0)
	s_andn2_b64 vcc, exec, s[36:37]
	s_cbranch_vccnz .LBB0_552
	s_add_i32 s88, s59, s74
	s_cmp_ge_i32 s88, 31
	s_cbranch_scc1 .Lfastf_sel
	v_add_u32_e32 v0, s74, v145
	v_cmp_lt_i32_e32 vcc, -1, v0
	s_and_b64 vcc, s[26:27], vcc
	s_nop 0
	v_cndmask_b32_e32 v2, v153, v16, vcc
	v_cmp_lt_i32_e32 vcc, 0, v0
	s_and_b64 vcc, s[26:27], vcc
	v_max_f32_e32 v174, v2, v2
	v_cndmask_b32_e32 v3, v153, v17, vcc
	v_cmp_lt_i32_e32 vcc, 1, v0
	s_and_b64 vcc, s[26:27], vcc
	s_nop 0
	v_cndmask_b32_e32 v4, v153, v18, vcc
	v_cmp_lt_i32_e32 vcc, 2, v0
	s_and_b64 vcc, s[26:27], vcc
	s_nop 0
	v_cndmask_b32_e32 v5, v153, v19, vcc
	v_cmp_lt_i32_e32 vcc, 7, v0
	s_and_b64 vcc, s[26:27], vcc
	s_nop 0
	v_cndmask_b32_e32 v6, v153, v20, vcc
	v_cmp_lt_i32_e32 vcc, 8, v0
	s_and_b64 vcc, s[26:27], vcc
	s_nop 0
	v_cndmask_b32_e32 v7, v153, v21, vcc
	v_cmp_lt_i32_e32 vcc, 9, v0
	s_and_b64 vcc, s[26:27], vcc
	s_nop 0
	v_cndmask_b32_e32 v8, v153, v22, vcc
	v_cmp_lt_i32_e32 vcc, 10, v0
	s_and_b64 vcc, s[26:27], vcc
	s_nop 0
	v_cndmask_b32_e32 v9, v153, v23, vcc
	v_cmp_lt_i32_e32 vcc, 15, v0
	s_and_b64 vcc, s[26:27], vcc
	s_nop 0
	v_cndmask_b32_e32 v10, v153, v24, vcc
	v_cmp_lt_i32_e32 vcc, 16, v0
	s_and_b64 vcc, s[26:27], vcc
	s_nop 0
	v_cndmask_b32_e32 v11, v153, v25, vcc
	v_cmp_lt_i32_e32 vcc, 17, v0
	s_and_b64 vcc, s[26:27], vcc
	s_nop 0
	v_cndmask_b32_e32 v12, v153, v26, vcc
	v_cmp_lt_i32_e32 vcc, 18, v0
	s_and_b64 vcc, s[26:27], vcc
	s_nop 0
	v_cndmask_b32_e32 v13, v153, v27, vcc
	v_cmp_lt_i32_e32 vcc, 23, v0
	s_and_b64 vcc, s[26:27], vcc
	s_nop 0
	v_cndmask_b32_e32 v14, v153, v28, vcc
	v_cmp_lt_i32_e32 vcc, 24, v0
	s_and_b64 vcc, s[26:27], vcc
	s_nop 0
	v_cndmask_b32_e32 v15, v153, v29, vcc
	v_cmp_lt_i32_e32 vcc, 25, v0
	s_and_b64 vcc, s[26:27], vcc
	s_nop 0
	v_cndmask_b32_e32 v176, v153, v30, vcc
	v_cmp_lt_i32_e32 vcc, 26, v0
	v_max_f32_e32 v0, v3, v3
	v_max_f32_e32 v0, v174, v0
	v_max3_f32 v0, v0, v4, v5
	v_max3_f32 v0, v0, v6, v7
	v_max3_f32 v0, v0, v8, v9
	v_max3_f32 v0, v0, v10, v11
	s_and_b64 vcc, s[26:27], vcc
	v_max3_f32 v0, v0, v12, v13
	v_cndmask_b32_e32 v177, v153, v31, vcc
	v_max3_f32 v0, v0, v14, v15
	v_max3_f32 v0, v0, v176, v177
	v_mov_b32_e32 v174, v0
	s_nop 1
	v_permlane32_swap_b32_e32 v0, v174
	v_max_f32_e32 v174, v174, v174
	v_max_f32_e32 v0, v0, v0
	v_max_f32_e32 v0, v0, v174
	v_mul_f32_e32 v0, 0x3e0293ee, v0
	v_add_f32_e32 v174, 0x41000000, v175
	v_cmp_gt_f32_e32 vcc, v0, v174
	s_nop 1
	v_cndmask_b32_e32 v174, v175, v0, vcc
	v_max_f32_e32 v0, v174, v174
	v_max_f32_e32 v178, 0xe0ad78ec, v0
	v_fma_f32 v0, v2, s52, -v178
	v_exp_f32_e32 v0, v0
	v_fma_f32 v2, v3, s52, -v178
	v_exp_f32_e32 v2, v2
	v_fma_f32 v3, v4, s52, -v178
	v_exp_f32_e32 v3, v3
	v_fma_f32 v4, v5, s52, -v178
	v_exp_f32_e32 v4, v4
	v_add_f32_e32 v5, 0, v0
	v_add_f32_e32 v5, v2, v5
	v_add_f32_e32 v5, v3, v5
	v_add_f32_e32 v179, v4, v5
	v_fma_f32 v5, v6, s52, -v178
	v_exp_f32_e32 v5, v5
	v_fma_f32 v6, v7, s52, -v178
	v_exp_f32_e32 v6, v6
	v_fma_f32 v7, v8, s52, -v178
	v_exp_f32_e32 v7, v7
	v_fma_f32 v8, v9, s52, -v178
	v_exp_f32_e32 v8, v8
	v_add_f32_e32 v9, v5, v179
	v_add_f32_e32 v9, v6, v9
	v_add_f32_e32 v9, v7, v9
	v_add_f32_e32 v179, v8, v9
	v_fma_f32 v9, v10, s52, -v178
	v_exp_f32_e32 v9, v9
	v_fma_f32 v10, v11, s52, -v178
	v_exp_f32_e32 v10, v10
	v_fma_f32 v11, v12, s52, -v178
	v_exp_f32_e32 v11, v11
	v_fma_f32 v12, v13, s52, -v178
	v_exp_f32_e32 v12, v12
	v_add_f32_e32 v13, v9, v179
	v_add_f32_e32 v13, v10, v13
	v_add_f32_e32 v13, v11, v13
	v_add_f32_e32 v179, v12, v13
	v_fma_f32 v13, v14, s52, -v178
	v_exp_f32_e32 v13, v13
	v_fma_f32 v14, v15, s52, -v178
	v_exp_f32_e32 v14, v14
	v_fma_f32 v15, v176, s52, -v178
	v_exp_f32_e32 v15, v15
	v_fma_f32 v176, v177, s52, -v178
	v_exp_f32_e32 v176, v176
	v_add_f32_e32 v177, v13, v179
	v_add_f32_e32 v177, v14, v177
	v_add_f32_e32 v177, v15, v177
	v_add_f32_e32 v177, v176, v177
	v_mov_b32_e32 v178, v177
	s_nop 1
	v_permlane32_swap_b32_e32 v177, v178
	s_cbranch_vccz .LBB0_551
	v_sub_f32_e32 v175, v175, v174
	v_exp_f32_e32 v180, v175
	s_nop 0
	v_mul_f32_e32 v163, v163, v180
	v_pk_mul_f32 v[94:95], v[94:95], v[180:181] op_sel_hi:[1,0]
	v_pk_mul_f32 v[92:93], v[92:93], v[180:181] op_sel_hi:[1,0]
	v_pk_mul_f32 v[90:91], v[90:91], v[180:181] op_sel_hi:[1,0]
	v_pk_mul_f32 v[88:89], v[88:89], v[180:181] op_sel_hi:[1,0]
	v_pk_mul_f32 v[86:87], v[86:87], v[180:181] op_sel_hi:[1,0]
	v_pk_mul_f32 v[84:85], v[84:85], v[180:181] op_sel_hi:[1,0]
	v_pk_mul_f32 v[82:83], v[82:83], v[180:181] op_sel_hi:[1,0]
	v_pk_mul_f32 v[80:81], v[80:81], v[180:181] op_sel_hi:[1,0]
	v_pk_mul_f32 v[78:79], v[78:79], v[180:181] op_sel_hi:[1,0]
	v_pk_mul_f32 v[76:77], v[76:77], v[180:181] op_sel_hi:[1,0]
	v_pk_mul_f32 v[74:75], v[74:75], v[180:181] op_sel_hi:[1,0]
	v_pk_mul_f32 v[72:73], v[72:73], v[180:181] op_sel_hi:[1,0]
	v_pk_mul_f32 v[70:71], v[70:71], v[180:181] op_sel_hi:[1,0]
	v_pk_mul_f32 v[68:69], v[68:69], v[180:181] op_sel_hi:[1,0]
	v_pk_mul_f32 v[66:67], v[66:67], v[180:181] op_sel_hi:[1,0]
	v_pk_mul_f32 v[64:65], v[64:65], v[180:181] op_sel_hi:[1,0]
	v_pk_mul_f32 v[62:63], v[62:63], v[180:181] op_sel_hi:[1,0]
	v_pk_mul_f32 v[60:61], v[60:61], v[180:181] op_sel_hi:[1,0]
	v_pk_mul_f32 v[58:59], v[58:59], v[180:181] op_sel_hi:[1,0]
	v_pk_mul_f32 v[56:57], v[56:57], v[180:181] op_sel_hi:[1,0]
	v_pk_mul_f32 v[54:55], v[54:55], v[180:181] op_sel_hi:[1,0]
	v_pk_mul_f32 v[52:53], v[52:53], v[180:181] op_sel_hi:[1,0]
	v_pk_mul_f32 v[50:51], v[50:51], v[180:181] op_sel_hi:[1,0]
	v_pk_mul_f32 v[48:49], v[48:49], v[180:181] op_sel_hi:[1,0]
	v_pk_mul_f32 v[46:47], v[46:47], v[180:181] op_sel_hi:[1,0]
	v_pk_mul_f32 v[44:45], v[44:45], v[180:181] op_sel_hi:[1,0]
	v_pk_mul_f32 v[42:43], v[42:43], v[180:181] op_sel_hi:[1,0]
	v_pk_mul_f32 v[40:41], v[40:41], v[180:181] op_sel_hi:[1,0]
	v_pk_mul_f32 v[38:39], v[38:39], v[180:181] op_sel_hi:[1,0]
	v_pk_mul_f32 v[36:37], v[36:37], v[180:181] op_sel_hi:[1,0]
	v_pk_mul_f32 v[34:35], v[34:35], v[180:181] op_sel_hi:[1,0]
	v_pk_mul_f32 v[32:33], v[32:33], v[180:181] op_sel_hi:[1,0]

; #define LAS __attribute__((address_space(3)))
; DI float xh_max(float x) { const unsigned u = __float_as_uint(x); const auto r = __builtin_amdgcn_permlane32_swap(u, u, false, false); return fmaxf(__uint_as_float(r[0]), __uint_as_float(r[1])); }
; DI float xh_sum(float x) { const unsigned u = __float_as_uint(x); const auto r = __builtin_amdgcn_permlane32_swap(u, u, false, false); return __uint_as_float(r[0]) + __uint_as_float(r[1]); }
; #define MFMA32(a, b, c) __builtin_amdgcn_mfma_f32_32x32x16_bf16((a), (b), (c), 0, 0, 0)
; DI f32x16 co_qk1(LAS unsigned char* st, const bf16x8 (&qf)[8], int ka_in) {
;     const int ka = ka_in;
;     f32x16 S;
; #pragma unroll
;     for (int i = 0; i < 16; ++i) S[i] = 0.f;
;     __builtin_amdgcn_s_setprio(1);
; #pragma unroll
;     for (int ks = 0; ks < 8; ++ks) { const bf16x8 a = *(const LAS bf16x8*)(st + (ka ^ (32 * ks))); S = MFMA32(a, qf[ks], S); }
;     __builtin_amdgcn_s_setprio(0);
;     return S;
; }
; template <int MODE>
; DI void co_finish(f32x16 S, LAS unsigned char* st, int key_base, AttnState& as, int tq, bool rowsel, int vb_in, int hh) {
;     const int vb = vb_in;
;     {
;         const int base = key_base + 4 * hh;
;         const int hi = (MODE == 0) ? (((tq - 31) >> 4) - base) : (tq - base);
;         const int lo = hi - 512;
; #pragma unroll
;         for (int i = 0; i < 16; ++i) { const int c = (i & 3) + 8 * (i >> 2); bool ok = (c <= hi); if (MODE == 2) ok = ok && (c > lo); if (MODE == 1) ok = ok && rowsel; S[i] = ok ? S[i] : -1e30f; }
;     }
;     float mx = S[0];
; #pragma unroll
;     for (int i = 1; i < 16; ++i) mx = fmaxf(mx, S[i]);
;     mx = xh_max(mx);
;     const float mxs = mx * SM_SCALE; const bool need = mxs > as.m + 8.f;
;     const float mnew = need ? mxs : as.m, muse = -fmaxf(mnew, -1e20f); float ps = 0.f;
; #pragma unroll
;     for (int i = 0; i < 16; ++i) { const float p = __builtin_amdgcn_exp2f(__builtin_fmaf(S[i], SM_SCALE, muse)); S[i] = p; ps += p; }
;     ps = xh_sum(ps);
;     if (__builtin_amdgcn_ballot_w64(need) != 0ull) {
;         const float alpha = __builtin_amdgcn_exp2f(as.m - mnew);
;         as.l *= alpha;
; #pragma unroll
;         for (int dt = 0; dt < 4; ++dt)
; #pragma unroll
;             for (int i = 0; i < 16; ++i) as.acc[dt][i] *= alpha;
;     }
;     as.l += ps; as.m = mnew;
.Lfs_sel:
	s_waitcnt lgkmcnt(0)
	v_add_u32_e32 v246, s40, v162
	ds_read_b128 v[238:241], v246
	v_add_u32_e32 v246, s40, v164
	ds_read_b128 v[242:245], v246
	v_add_u32_e32 v0, s74, v145
	v_cmp_lt_i32_e32 vcc, -1, v0
	s_and_b64 vcc, s[26:27], vcc
	s_nop 0
	v_cndmask_b32_e32 v2, v153, v16, vcc
	v_cmp_lt_i32_e32 vcc, 0, v0
	s_and_b64 vcc, s[26:27], vcc
	v_max_f32_e32 v174, v2, v2
	v_cndmask_b32_e32 v3, v153, v17, vcc
	v_cmp_lt_i32_e32 vcc, 1, v0
	s_and_b64 vcc, s[26:27], vcc
	s_nop 0
	v_cndmask_b32_e32 v4, v153, v18, vcc
	s_waitcnt lgkmcnt(1)
	v_mfma_f32_32x32x16_bf16 v[96:111], v[238:241], v[112:115], 0
	v_add_u32_e32 v246, s40, v165
	ds_read_b128 v[238:241], v246
	v_cmp_lt_i32_e32 vcc, 2, v0
	s_and_b64 vcc, s[26:27], vcc
	s_nop 0
	v_cndmask_b32_e32 v5, v153, v19, vcc
	v_cmp_lt_i32_e32 vcc, 7, v0
	s_and_b64 vcc, s[26:27], vcc
	s_nop 0
	v_cndmask_b32_e32 v6, v153, v20, vcc
	v_cmp_lt_i32_e32 vcc, 8, v0
	s_and_b64 vcc, s[26:27], vcc
	s_nop 0
	v_cndmask_b32_e32 v7, v153, v21, vcc
	v_cmp_lt_i32_e32 vcc, 9, v0
	s_and_b64 vcc, s[26:27], vcc
	s_waitcnt lgkmcnt(1)
	v_mfma_f32_32x32x16_bf16 v[96:111], v[242:245], v[116:119], v[96:111]
	v_add_u32_e32 v246, s40, v166
	ds_read_b128 v[242:245], v246
	s_nop 0
	v_cndmask_b32_e32 v8, v153, v22, vcc
	v_cmp_lt_i32_e32 vcc, 10, v0
	s_and_b64 vcc, s[26:27], vcc
	s_nop 0
	v_cndmask_b32_e32 v9, v153, v23, vcc
	v_cmp_lt_i32_e32 vcc, 15, v0
	s_and_b64 vcc, s[26:27], vcc
	s_nop 0
	v_cndmask_b32_e32 v10, v153, v24, vcc
	v_cmp_lt_i32_e32 vcc, 16, v0
	s_and_b64 vcc, s[26:27], vcc
	s_nop 0
	v_cndmask_b32_e32 v11, v153, v25, vcc
	s_waitcnt lgkmcnt(1)
	v_mfma_f32_32x32x16_bf16 v[96:111], v[238:241], v[120:123], v[96:111]
	v_add_u32_e32 v246, s40, v167
	ds_read_b128 v[238:241], v246
	v_cmp_lt_i32_e32 vcc, 17, v0
	s_and_b64 vcc, s[26:27], vcc
	s_nop 0
	v_cndmask_b32_e32 v12, v153, v26, vcc
	v_cmp_lt_i32_e32 vcc, 18, v0
	s_and_b64 vcc, s[26:27], vcc
	s_nop 0
	v_cndmask_b32_e32 v13, v153, v27, vcc
	v_cmp_lt_i32_e32 vcc, 23, v0
	s_and_b64 vcc, s[26:27], vcc
	s_nop 0
	v_cndmask_b32_e32 v14, v153, v28, vcc
	v_cmp_lt_i32_e32 vcc, 24, v0
	s_waitcnt lgkmcnt(1)
	v_mfma_f32_32x32x16_bf16 v[96:111], v[242:245], v[124:127], v[96:111]
	v_add_u32_e32 v246, s40, v168
	ds_read_b128 v[242:245], v246
	s_and_b64 vcc, s[26:27], vcc
	s_nop 0
	v_cndmask_b32_e32 v15, v153, v29, vcc
	v_cmp_lt_i32_e32 vcc, 25, v0
	s_and_b64 vcc, s[26:27], vcc
	s_nop 0
	v_cndmask_b32_e32 v176, v153, v30, vcc
	v_cmp_lt_i32_e32 vcc, 26, v0
	v_max_f32_e32 v0, v3, v3
	v_max_f32_e32 v0, v174, v0
	v_max3_f32 v0, v0, v4, v5
	v_max3_f32 v0, v0, v6, v7
	v_max3_f32 v0, v0, v8, v9
	v_max3_f32 v0, v0, v10, v11
	s_waitcnt lgkmcnt(1)
	v_mfma_f32_32x32x16_bf16 v[96:111], v[238:241], v[128:131], v[96:111]
	v_add_u32_e32 v246, s40, v169
	ds_read_b128 v[238:241], v246
	s_and_b64 vcc, s[26:27], vcc
	v_max3_f32 v0, v0, v12, v13
	v_cndmask_b32_e32 v177, v153, v31, vcc
	v_max3_f32 v0, v0, v14, v15
	v_max3_f32 v0, v0, v176, v177
	v_mov_b32_e32 v174, v0
	s_nop 1
	v_permlane32_swap_b32_e32 v0, v174
	v_max_f32_e32 v174, v174, v174
	v_max_f32_e32 v0, v0, v0
	v_max_f32_e32 v0, v0, v174
	v_mul_f32_e32 v0, 0x3e0293ee, v0
	v_add_f32_e32 v174, 0x41000000, v175
	v_cmp_gt_f32_e32 vcc, v0, v174
	s_waitcnt lgkmcnt(1)
	v_mfma_f32_32x32x16_bf16 v[96:111], v[242:245], v[132:135], v[96:111]
	v_add_u32_e32 v246, s40, v170
	ds_read_b128 v[242:245], v246
	s_nop 1
	v_cndmask_b32_e32 v174, v175, v0, vcc
	v_max_f32_e32 v0, v174, v174
	v_max_f32_e32 v178, 0xe0ad78ec, v0
	v_fma_f32 v0, v2, s52, -v178
	v_exp_f32_e32 v0, v0
	v_fma_f32 v2, v3, s52, -v178
	v_exp_f32_e32 v2, v2
	v_fma_f32 v3, v4, s52, -v178
	v_exp_f32_e32 v3, v3
	v_fma_f32 v4, v5, s52, -v178
	v_exp_f32_e32 v4, v4
	v_add_f32_e32 v5, 0, v0
	s_waitcnt lgkmcnt(1)
	v_mfma_f32_32x32x16_bf16 v[96:111], v[238:241], v[136:139], v[96:111]
	v_add_f32_e32 v5, v2, v5
	v_add_f32_e32 v5, v3, v5
	v_add_f32_e32 v179, v4, v5
	v_fma_f32 v5, v6, s52, -v178
	v_exp_f32_e32 v5, v5
	v_fma_f32 v6, v7, s52, -v178
	v_exp_f32_e32 v6, v6
	v_fma_f32 v7, v8, s52, -v178
	v_exp_f32_e32 v7, v7
	v_fma_f32 v8, v9, s52, -v178
	v_exp_f32_e32 v8, v8
	v_add_f32_e32 v9, v5, v179
	v_add_f32_e32 v9, v6, v9
	v_add_f32_e32 v9, v7, v9
	s_waitcnt lgkmcnt(0)
	v_mfma_f32_32x32x16_bf16 v[96:111], v[242:245], v[140:143], v[96:111]
	v_add_f32_e32 v179, v8, v9
	v_fma_f32 v9, v10, s52, -v178
	v_exp_f32_e32 v9, v9
	v_fma_f32 v10, v11, s52, -v178
	v_exp_f32_e32 v10, v10
	v_fma_f32 v11, v12, s52, -v178
	v_exp_f32_e32 v11, v11
	v_fma_f32 v12, v13, s52, -v178
	v_exp_f32_e32 v12, v12
	v_add_f32_e32 v13, v9, v179
	v_add_f32_e32 v13, v10, v13
	v_add_f32_e32 v13, v11, v13
	v_add_f32_e32 v179, v12, v13
	v_fma_f32 v13, v14, s52, -v178
	v_exp_f32_e32 v13, v13
	v_fma_f32 v14, v15, s52, -v178
	v_exp_f32_e32 v14, v14
	v_fma_f32 v15, v176, s52, -v178
	v_exp_f32_e32 v15, v15
	v_fma_f32 v176, v177, s52, -v178
	v_exp_f32_e32 v176, v176
	v_add_f32_e32 v177, v13, v179
	v_add_f32_e32 v177, v14, v177
	v_add_f32_e32 v177, v15, v177
	v_add_f32_e32 v177, v176, v177
	v_mov_b32_e32 v178, v177
	s_nop 1
	v_permlane32_swap_b32_e32 v177, v178
	s_cbranch_vccz .Lfs_sel_551
; template <int MODE>
; DI void co_finish(f32x16 S, LAS unsigned char* st, int key_base, AttnState& as, int tq, bool rowsel, int vb_in, int hh) {
;     ...
;     if (__builtin_amdgcn_ballot_w64(need) != 0ull) {
;         const float alpha = __builtin_amdgcn_exp2f(as.m - mnew);
;         as.l *= alpha;
; #pragma unroll
;         for (int dt = 0; dt < 4; ++dt)
; #pragma unroll
;             for (int i = 0; i < 16; ++i) as.acc[dt][i] *= alpha;
;     }
	v_sub_f32_e32 v175, v175, v174
	v_exp_f32_e32 v180, v175
	s_nop 0
	v_mul_f32_e32 v163, v163, v180
	v_pk_mul_f32 v[94:95], v[94:95], v[180:181] op_sel_hi:[1,0]
	v_pk_mul_f32 v[92:93], v[92:93], v[180:181] op_sel_hi:[1,0]
	v_pk_mul_f32 v[90:91], v[90:91], v[180:181] op_sel_hi:[1,0]
	v_pk_mul_f32 v[88:89], v[88:89], v[180:181] op_sel_hi:[1,0]
	v_pk_mul_f32 v[86:87], v[86:87], v[180:181] op_sel_hi:[1,0]
	v_pk_mul_f32 v[84:85], v[84:85], v[180:181] op_sel_hi:[1,0]
	v_pk_mul_f32 v[82:83], v[82:83], v[180:181] op_sel_hi:[1,0]
	v_pk_mul_f32 v[80:81], v[80:81], v[180:181] op_sel_hi:[1,0]
	v_pk_mul_f32 v[78:79], v[78:79], v[180:181] op_sel_hi:[1,0]
	v_pk_mul_f32 v[76:77], v[76:77], v[180:181] op_sel_hi:[1,0]
	v_pk_mul_f32 v[74:75], v[74:75], v[180:181] op_sel_hi:[1,0]
	v_pk_mul_f32 v[72:73], v[72:73], v[180:181] op_sel_hi:[1,0]
	v_pk_mul_f32 v[70:71], v[70:71], v[180:181] op_sel_hi:[1,0]
	v_pk_mul_f32 v[68:69], v[68:69], v[180:181] op_sel_hi:[1,0]
	v_pk_mul_f32 v[66:67], v[66:67], v[180:181] op_sel_hi:[1,0]
	v_pk_mul_f32 v[64:65], v[64:65], v[180:181] op_sel_hi:[1,0]
	v_pk_mul_f32 v[62:63], v[62:63], v[180:181] op_sel_hi:[1,0]
	v_pk_mul_f32 v[60:61], v[60:61], v[180:181] op_sel_hi:[1,0]
	v_pk_mul_f32 v[58:59], v[58:59], v[180:181] op_sel_hi:[1,0]
	v_pk_mul_f32 v[56:57], v[56:57], v[180:181] op_sel_hi:[1,0]
	v_pk_mul_f32 v[54:55], v[54:55], v[180:181] op_sel_hi:[1,0]
	v_pk_mul_f32 v[52:53], v[52:53], v[180:181] op_sel_hi:[1,0]
	v_pk_mul_f32 v[50:51], v[50:51], v[180:181] op_sel_hi:[1,0]
	v_pk_mul_f32 v[48:49], v[48:49], v[180:181] op_sel_hi:[1,0]
	v_pk_mul_f32 v[46:47], v[46:47], v[180:181] op_sel_hi:[1,0]
	v_pk_mul_f32 v[44:45], v[44:45], v[180:181] op_sel_hi:[1,0]
	v_pk_mul_f32 v[42:43], v[42:43], v[180:181] op_sel_hi:[1,0]
	v_pk_mul_f32 v[40:41], v[40:41], v[180:181] op_sel_hi:[1,0]
	v_pk_mul_f32 v[38:39], v[38:39], v[180:181] op_sel_hi:[1,0]
	v_pk_mul_f32 v[36:37], v[36:37], v[180:181] op_sel_hi:[1,0]
	v_pk_mul_f32 v[34:35], v[34:35], v[180:181] op_sel_hi:[1,0]
	v_pk_mul_f32 v[32:33], v[32:33], v[180:181] op_sel_hi:[1,0]

; #define LAS __attribute__((address_space(3)))
; DI float xh_max(float x) { const unsigned u = __float_as_uint(x); const auto r = __builtin_amdgcn_permlane32_swap(u, u, false, false); return fmaxf(__uint_as_float(r[0]), __uint_as_float(r[1])); }
; DI float xh_sum(float x) { const unsigned u = __float_as_uint(x); const auto r = __builtin_amdgcn_permlane32_swap(u, u, false, false); return __uint_as_float(r[0]) + __uint_as_float(r[1]); }
; #define MFMA32(a, b, c) __builtin_amdgcn_mfma_f32_32x32x16_bf16((a), (b), (c), 0, 0, 0)
; DI f32x16 co_qk1(LAS unsigned char* st, const bf16x8 (&qf)[8], int ka_in) {
;     const int ka = ka_in;
;     f32x16 S;
; #pragma unroll
;     for (int i = 0; i < 16; ++i) S[i] = 0.f;
;     __builtin_amdgcn_s_setprio(1);
; #pragma unroll
;     for (int ks = 0; ks < 8; ++ks) { const bf16x8 a = *(const LAS bf16x8*)(st + (ka ^ (32 * ks))); S = MFMA32(a, qf[ks], S); }
;     __builtin_amdgcn_s_setprio(0);
;     return S;
; }
; template <int MODE>
; DI void co_finish(f32x16 S, LAS unsigned char* st, int key_base, AttnState& as, int tq, bool rowsel, int vb_in, int hh) {
;     const int vb = vb_in;
;     {
;         const int base = key_base + 4 * hh;
;         const int hi = (MODE == 0) ? (((tq - 31) >> 4) - base) : (tq - base);
;         const int lo = hi - 512;
; #pragma unroll
;         for (int i = 0; i < 16; ++i) { const int c = (i & 3) + 8 * (i >> 2); bool ok = (c <= hi); if (MODE == 2) ok = ok && (c > lo); if (MODE == 1) ok = ok && rowsel; S[i] = ok ? S[i] : -1e30f; }
;     }
;     float mx = S[0];
; #pragma unroll
;     for (int i = 1; i < 16; ++i) mx = fmaxf(mx, S[i]);
;     mx = xh_max(mx);
;     const float mxs = mx * SM_SCALE; const bool need = mxs > as.m + 8.f;
;     const float mnew = need ? mxs : as.m, muse = -fmaxf(mnew, -1e20f); float ps = 0.f;
; #pragma unroll
;     for (int i = 0; i < 16; ++i) { const float p = __builtin_amdgcn_exp2f(__builtin_fmaf(S[i], SM_SCALE, muse)); S[i] = p; ps += p; }
;     ps = xh_sum(ps);
;     if (__builtin_amdgcn_ballot_w64(need) != 0ull) {
;         const float alpha = __builtin_amdgcn_exp2f(as.m - mnew);
;         as.l *= alpha;
; #pragma unroll
;         for (int dt = 0; dt < 4; ++dt)
; #pragma unroll
;             for (int i = 0; i < 16; ++i) as.acc[dt][i] *= alpha;
;     }
;     as.l += ps; as.m = mnew;
.Lfs_win:
	s_waitcnt lgkmcnt(0)
	v_add_u32_e32 v246, s16, v162
	ds_read_b128 v[238:241], v246
	v_add_u32_e32 v246, s16, v164
	ds_read_b128 v[242:245], v246
	v_add_u32_e32 v0, s79, v145
	v_cmp_gt_u32_e32 vcc, s53, v0
	v_add_u32_e32 v3, -1, v0
	v_add_u32_e32 v4, -2, v0
	v_cndmask_b32_e32 v2, v153, v16, vcc
	v_cmp_gt_u32_e32 vcc, s53, v3
	v_add_u32_e32 v5, -3, v0
	v_add_u32_e32 v6, -8, v0
	v_cndmask_b32_e32 v3, v153, v17, vcc
	v_cmp_gt_u32_e32 vcc, s53, v4
	v_add_u32_e32 v7, -9, v0
	v_add_u32_e32 v8, -10, v0
	v_cndmask_b32_e32 v4, v153, v18, vcc
	s_waitcnt lgkmcnt(1)
	v_mfma_f32_32x32x16_bf16 v[96:111], v[238:241], v[112:115], 0
	v_add_u32_e32 v246, s16, v165
	ds_read_b128 v[238:241], v246
	v_cmp_gt_u32_e32 vcc, s53, v5
	v_add_u32_e32 v9, -11, v0
	v_add_u32_e32 v10, -16, v0
	v_cndmask_b32_e32 v5, v153, v19, vcc
	v_cmp_gt_u32_e32 vcc, s53, v6
	v_subrev_u32_e32 v11, 17, v0
	v_subrev_u32_e32 v12, 18, v0
	v_cndmask_b32_e32 v6, v153, v20, vcc
	v_cmp_gt_u32_e32 vcc, s53, v7
	v_subrev_u32_e32 v13, 19, v0
	v_subrev_u32_e32 v14, 24, v0
	v_cndmask_b32_e32 v7, v153, v21, vcc
	v_cmp_gt_u32_e32 vcc, s53, v8
	s_waitcnt lgkmcnt(1)
	v_mfma_f32_32x32x16_bf16 v[96:111], v[242:245], v[116:119], v[96:111]
	v_add_u32_e32 v246, s16, v166
	ds_read_b128 v[242:245], v246
	v_subrev_u32_e32 v15, 25, v0
	v_subrev_u32_e32 v176, 26, v0
	v_cndmask_b32_e32 v8, v153, v22, vcc
	v_cmp_gt_u32_e32 vcc, s53, v9
	v_subrev_u32_e32 v0, 27, v0
	s_nop 0
	v_cndmask_b32_e32 v9, v153, v23, vcc
	v_cmp_gt_u32_e32 vcc, s53, v10
	s_nop 1
	v_cndmask_b32_e32 v10, v153, v24, vcc
	v_cmp_gt_u32_e32 vcc, s53, v11
	s_nop 1
	v_cndmask_b32_e32 v11, v153, v25, vcc
	s_waitcnt lgkmcnt(1)
	v_mfma_f32_32x32x16_bf16 v[96:111], v[238:241], v[120:123], v[96:111]
	v_add_u32_e32 v246, s16, v167
	ds_read_b128 v[238:241], v246
	v_cmp_gt_u32_e32 vcc, s53, v12
	s_nop 1
	v_cndmask_b32_e32 v12, v153, v26, vcc
	v_cmp_gt_u32_e32 vcc, s53, v13
	s_nop 1
	v_cndmask_b32_e32 v13, v153, v27, vcc
	v_cmp_gt_u32_e32 vcc, s53, v14
	s_nop 1
	v_cndmask_b32_e32 v14, v153, v28, vcc
	v_cmp_gt_u32_e32 vcc, s53, v15
	s_nop 1
	v_cndmask_b32_e32 v15, v153, v29, vcc
	v_cmp_gt_u32_e32 vcc, s53, v176
	s_waitcnt lgkmcnt(1)
	v_mfma_f32_32x32x16_bf16 v[96:111], v[242:245], v[124:127], v[96:111]
	v_add_u32_e32 v246, s16, v168
	ds_read_b128 v[242:245], v246
	v_max_f32_e32 v176, v3, v3
	s_nop 0
	v_cndmask_b32_e32 v178, v153, v30, vcc
	v_cmp_gt_u32_e32 vcc, s53, v0
	v_max_f32_e32 v0, v2, v2
	v_max_f32_e32 v0, v0, v176
	v_max3_f32 v0, v0, v4, v5
	v_max3_f32 v0, v0, v6, v7
	v_max3_f32 v0, v0, v8, v9
	v_max3_f32 v0, v0, v10, v11
	v_max3_f32 v0, v0, v12, v13
	v_cndmask_b32_e32 v179, v153, v31, vcc
	v_max3_f32 v0, v0, v14, v15
	s_waitcnt lgkmcnt(1)
	v_mfma_f32_32x32x16_bf16 v[96:111], v[238:241], v[128:131], v[96:111]
	v_add_u32_e32 v246, s16, v169
	ds_read_b128 v[238:241], v246
	v_max3_f32 v0, v0, v178, v179
	v_mov_b32_e32 v176, v0
	s_nop 1
	v_permlane32_swap_b32_e32 v0, v176
	v_max_f32_e32 v176, v176, v176
	v_max_f32_e32 v0, v0, v0
	v_max_f32_e32 v0, v0, v176
	v_mul_f32_e32 v0, 0x3e0293ee, v0
	v_add_f32_e32 v176, 0x41000000, v177
	v_cmp_gt_f32_e32 vcc, v0, v176
	s_nop 1
	v_cndmask_b32_e32 v176, v177, v0, vcc
	v_max_f32_e32 v0, v176, v176
	s_waitcnt lgkmcnt(1)
	v_mfma_f32_32x32x16_bf16 v[96:111], v[242:245], v[132:135], v[96:111]
	v_add_u32_e32 v246, s16, v170
	ds_read_b128 v[242:245], v246
	v_max_f32_e32 v180, 0xe0ad78ec, v0
	v_fma_f32 v0, v2, s52, -v180
	v_exp_f32_e32 v0, v0
	v_fma_f32 v2, v3, s52, -v180
	v_exp_f32_e32 v2, v2
	v_fma_f32 v3, v4, s52, -v180
	v_exp_f32_e32 v3, v3
	v_fma_f32 v4, v5, s52, -v180
	v_exp_f32_e32 v4, v4
	v_add_f32_e32 v5, 0, v0
	v_add_f32_e32 v5, v2, v5
	v_add_f32_e32 v5, v3, v5
	v_add_f32_e32 v181, v4, v5
	s_waitcnt lgkmcnt(1)
	v_mfma_f32_32x32x16_bf16 v[96:111], v[238:241], v[136:139], v[96:111]
	v_fma_f32 v5, v6, s52, -v180
	v_exp_f32_e32 v5, v5
	v_fma_f32 v6, v7, s52, -v180
	v_exp_f32_e32 v6, v6
	v_fma_f32 v7, v8, s52, -v180
	v_exp_f32_e32 v7, v7
	v_fma_f32 v8, v9, s52, -v180
	v_exp_f32_e32 v8, v8
	v_add_f32_e32 v9, v5, v181
	v_add_f32_e32 v9, v6, v9
	v_add_f32_e32 v9, v7, v9
	v_add_f32_e32 v181, v8, v9
	v_fma_f32 v9, v10, s52, -v180
	s_waitcnt lgkmcnt(0)
	v_mfma_f32_32x32x16_bf16 v[96:111], v[242:245], v[140:143], v[96:111]
	v_exp_f32_e32 v9, v9
	v_fma_f32 v10, v11, s52, -v180
	v_exp_f32_e32 v10, v10
	v_fma_f32 v11, v12, s52, -v180
	v_exp_f32_e32 v11, v11
	v_fma_f32 v12, v13, s52, -v180
	v_exp_f32_e32 v12, v12
	v_add_f32_e32 v13, v9, v181
	v_add_f32_e32 v13, v10, v13
	v_add_f32_e32 v13, v11, v13
	v_add_f32_e32 v181, v12, v13
	v_fma_f32 v13, v14, s52, -v180
	v_exp_f32_e32 v13, v13
	v_fma_f32 v14, v15, s52, -v180
	v_exp_f32_e32 v14, v14
	v_fma_f32 v15, v178, s52, -v180
	v_exp_f32_e32 v15, v15
	v_fma_f32 v178, v179, s52, -v180
	v_exp_f32_e32 v178, v178
	v_add_f32_e32 v179, v13, v181
	v_add_f32_e32 v179, v14, v179
	v_add_f32_e32 v179, v15, v179
	v_add_f32_e32 v179, v178, v179
	v_mov_b32_e32 v180, v179
	s_nop 1
	v_permlane32_swap_b32_e32 v179, v180
	s_cbranch_vccz .Lfs_win_520
	v_sub_f32_e32 v177, v177, v176
	v_exp_f32_e32 v182, v177
	s_nop 0
	v_mul_f32_e32 v175, v175, v182
	v_pk_mul_f32 v[94:95], v[94:95], v[182:183] op_sel_hi:[1,0]
	v_pk_mul_f32 v[92:93], v[92:93], v[182:183] op_sel_hi:[1,0]
	v_pk_mul_f32 v[90:91], v[90:91], v[182:183] op_sel_hi:[1,0]
	v_pk_mul_f32 v[88:89], v[88:89], v[182:183] op_sel_hi:[1,0]
	v_pk_mul_f32 v[86:87], v[86:87], v[182:183] op_sel_hi:[1,0]
	v_pk_mul_f32 v[84:85], v[84:85], v[182:183] op_sel_hi:[1,0]
	v_pk_mul_f32 v[82:83], v[82:83], v[182:183] op_sel_hi:[1,0]
	v_pk_mul_f32 v[80:81], v[80:81], v[182:183] op_sel_hi:[1,0]
	v_pk_mul_f32 v[78:79], v[78:79], v[182:183] op_sel_hi:[1,0]
	v_pk_mul_f32 v[76:77], v[76:77], v[182:183] op_sel_hi:[1,0]
	v_pk_mul_f32 v[74:75], v[74:75], v[182:183] op_sel_hi:[1,0]
	v_pk_mul_f32 v[72:73], v[72:73], v[182:183] op_sel_hi:[1,0]
	v_pk_mul_f32 v[70:71], v[70:71], v[182:183] op_sel_hi:[1,0]
	v_pk_mul_f32 v[68:69], v[68:69], v[182:183] op_sel_hi:[1,0]
	v_pk_mul_f32 v[66:67], v[66:67], v[182:183] op_sel_hi:[1,0]
	v_pk_mul_f32 v[64:65], v[64:65], v[182:183] op_sel_hi:[1,0]
	v_pk_mul_f32 v[62:63], v[62:63], v[182:183] op_sel_hi:[1,0]
	v_pk_mul_f32 v[60:61], v[60:61], v[182:183] op_sel_hi:[1,0]
	v_pk_mul_f32 v[58:59], v[58:59], v[182:183] op_sel_hi:[1,0]
	v_pk_mul_f32 v[56:57], v[56:57], v[182:183] op_sel_hi:[1,0]
	v_pk_mul_f32 v[54:55], v[54:55], v[182:183] op_sel_hi:[1,0]
	v_pk_mul_f32 v[52:53], v[52:53], v[182:183] op_sel_hi:[1,0]
	v_pk_mul_f32 v[50:51], v[50:51], v[182:183] op_sel_hi:[1,0]
	v_pk_mul_f32 v[48:49], v[48:49], v[182:183] op_sel_hi:[1,0]
	v_pk_mul_f32 v[46:47], v[46:47], v[182:183] op_sel_hi:[1,0]
	v_pk_mul_f32 v[44:45], v[44:45], v[182:183] op_sel_hi:[1,0]
	v_pk_mul_f32 v[42:43], v[42:43], v[182:183] op_sel_hi:[1,0]
	v_pk_mul_f32 v[40:41], v[40:41], v[182:183] op_sel_hi:[1,0]
	v_pk_mul_f32 v[38:39], v[38:39], v[182:183] op_sel_hi:[1,0]
	v_pk_mul_f32 v[36:37], v[36:37], v[182:183] op_sel_hi:[1,0]
	v_pk_mul_f32 v[34:35], v[34:35], v[182:183] op_sel_hi:[1,0]
	v_pk_mul_f32 v[32:33], v[32:33], v[182:183] op_sel_hi:[1,0]
